# static s_setprio 1 for waves 0-3 instead (other half), flips removed
# speedup vs baseline: 1.0113x; 1.0056x over previous
_Z6mk_fwd6Params:
	s_load_dwordx2 s[42:43], s[0:1], 0xe8
	s_add_u32 s8, s0, 0xe8
	v_and_b32_e32 v1, 0x3ff, v0
	s_addc_u32 s9, s1, 0
	v_readfirstlane_b32 s68, v1
	s_nop 3
	s_lshr_b32 s98, s68, 6
	s_cmp_lt_u32 s98, 4
	s_cbranch_scc0 .Lprio_static_done
	s_setprio 1
